# v45 + packed f32 ops of the attention prologue region also unpacked into scalar f32 pairs
# baseline (speedup 1.0000x reference)
.LBB0_167:
	v_add_u32_e32 v49, s52, v38
	ds_read_b32 v70, v49
	v_add_u32_e32 v74, s52, v32
	ds_read_b128 v[50:53], v74
	ds_read_b128 v[54:57], v74 offset:16
	ds_read_b128 v[58:61], v74 offset:32
	ds_read_b128 v[62:65], v74 offset:48
	ds_read_b128 v[66:69], v74 offset:16384
	s_addk_i32 s52, 0x400
	s_cmpk_eq_i32 s52, 0x2000
	s_waitcnt lgkmcnt(5)
	v_add_f32_e64 v10, v10, -v70
	v_add_f32_e64 v11, v11, -v70
	v_add_f32_e64 v12, v12, -v70
	v_add_f32_e64 v13, v13, -v70
	s_waitcnt lgkmcnt(4)
	v_fma_f32 v72, v10, v50, v70
	v_fma_f32 v73, v11, v51, v70
	v_add_f32_e64 v14, v14, -v70
	v_add_f32_e64 v15, v15, -v70
	s_waitcnt lgkmcnt(0)
	v_fma_f32 v10, v72, v66, 0
	v_fma_f32 v11, v73, v67, 0
	v_fma_f32 v66, v12, v52, v70
	v_fma_f32 v67, v13, v53, v70
	v_fma_f32 v54, v14, v54, v70
	v_fma_f32 v55, v15, v55, v70
	v_fma_f32 v50, v66, v68, v10
	v_fma_f32 v51, v67, v69, v11
	ds_read_b128 v[10:13], v74 offset:16400
	v_add_f32_e64 v14, v16, -v70
	v_add_f32_e64 v15, v17, -v70
	v_add_f32_e64 v16, v18, -v70
	v_add_f32_e64 v17, v19, -v70
	v_fma_f32 v56, v14, v56, v70
	v_fma_f32 v57, v15, v57, v70
	v_fma_f32 v58, v16, v58, v70
	v_fma_f32 v59, v17, v59, v70
	s_waitcnt lgkmcnt(0)
	v_fma_f32 v10, v54, v10, v50
	v_fma_f32 v11, v55, v11, v51
	v_add_f32_e64 v16, v22, -v70
	v_add_f32_e64 v17, v23, -v70
	v_fma_f32 v14, v56, v12, v10
	v_fma_f32 v15, v57, v13, v11
	ds_read_b128 v[10:13], v74 offset:16416
	v_fma_f32 v62, v16, v62, v70
	v_fma_f32 v63, v17, v63, v70
	s_waitcnt lgkmcnt(0)
	v_fma_f32 v10, v58, v10, v14
	v_fma_f32 v11, v59, v11, v15
	v_add_f32_e64 v14, v20, -v70
	v_add_f32_e64 v15, v21, -v70
	s_nop 0
	v_fma_f32 v60, v14, v60, v70
	v_fma_f32 v61, v15, v61, v70
	s_nop 0
	v_fma_f32 v14, v60, v12, v10
	v_fma_f32 v15, v61, v13, v11
	ds_read_b128 v[10:13], v74 offset:16432
	s_waitcnt lgkmcnt(0)
	v_fma_f32 v10, v62, v10, v14
	v_fma_f32 v11, v63, v11, v15
	v_add_f32_e64 v14, v24, -v70
	v_add_f32_e64 v15, v25, -v70
	s_nop 0
	v_fma_f32 v64, v14, v64, v70
	v_fma_f32 v65, v15, v65, v70
	s_nop 0
	v_fma_f32 v10, v64, v12, v10
	v_fma_f32 v11, v65, v13, v11
	s_nop 0
	v_add_f32_e32 v10, v10, v11
	ds_write_b32 v48, v10
	ds_read_b32 v68, v49 offset:256
	ds_read_b128 v[10:13], v74 offset:256
	ds_read_b128 v[14:17], v74 offset:272
	ds_read_b128 v[18:21], v74 offset:288
	ds_read_b128 v[22:25], v74 offset:304
	ds_read_b128 v[50:53], v74 offset:16640
	s_waitcnt lgkmcnt(5)
	v_add_f32_e64 v70, v72, -v68
	v_add_f32_e64 v71, v73, -v68
	s_waitcnt lgkmcnt(4)
	v_fma_f32 v70, v70, v10, v68
	v_fma_f32 v71, v71, v11, v68
	s_waitcnt lgkmcnt(0)
	v_fma_f32 v10, v70, v50, 0
	v_fma_f32 v11, v71, v51, 0
	v_add_f32_e64 v50, v66, -v68
	v_add_f32_e64 v51, v67, -v68
	s_nop 0
	v_fma_f32 v66, v50, v12, v68
	v_fma_f32 v67, v51, v13, v68
	s_nop 0
	v_fma_f32 v50, v66, v52, v10
	v_fma_f32 v51, v67, v53, v11
	ds_read_b128 v[10:13], v74 offset:16656
	v_add_f32_e64 v52, v54, -v68
	v_add_f32_e64 v53, v55, -v68
	s_nop 0
	v_fma_f32 v54, v52, v14, v68
	v_fma_f32 v55, v53, v15, v68
	v_add_f32_e64 v14, v56, -v68
	v_add_f32_e64 v15, v57, -v68
	s_waitcnt lgkmcnt(0)
	v_fma_f32 v10, v54, v10, v50
	v_fma_f32 v11, v55, v11, v51
	v_fma_f32 v56, v14, v16, v68
	v_fma_f32 v57, v15, v17, v68
	v_add_f32_e64 v16, v58, -v68
	v_add_f32_e64 v17, v59, -v68
	v_fma_f32 v14, v56, v12, v10
	v_fma_f32 v15, v57, v13, v11
	ds_read_b128 v[10:13], v74 offset:16672
	v_fma_f32 v58, v16, v18, v68
	v_fma_f32 v59, v17, v19, v68
	v_add_f32_e64 v16, v62, -v68
	v_add_f32_e64 v17, v63, -v68
	s_waitcnt lgkmcnt(0)
	v_fma_f32 v10, v58, v10, v14
	v_fma_f32 v11, v59, v11, v15
	v_add_f32_e64 v14, v60, -v68
	v_add_f32_e64 v15, v61, -v68
	v_fma_f32 v62, v16, v22, v68
	v_fma_f32 v63, v17, v23, v68
	v_fma_f32 v60, v14, v20, v68
	v_fma_f32 v61, v15, v21, v68
	s_nop 0
	v_fma_f32 v14, v60, v12, v10
	v_fma_f32 v15, v61, v13, v11
	ds_read_b128 v[10:13], v74 offset:16688
	s_waitcnt lgkmcnt(0)
	v_fma_f32 v10, v62, v10, v14
	v_fma_f32 v11, v63, v11, v15
	v_add_f32_e64 v14, v64, -v68
	v_add_f32_e64 v15, v65, -v68
	s_nop 0
	v_fma_f32 v64, v14, v24, v68
	v_fma_f32 v65, v15, v25, v68
	s_nop 0
	v_fma_f32 v10, v64, v12, v10
	v_fma_f32 v11, v65, v13, v11
	s_nop 0
	v_add_f32_e32 v10, v10, v11
	ds_write_b32 v48, v10 offset:1024
	ds_read_b32 v68, v49 offset:512
	ds_read_b128 v[10:13], v74 offset:512
	ds_read_b128 v[14:17], v74 offset:528
	ds_read_b128 v[18:21], v74 offset:544
	ds_read_b128 v[22:25], v74 offset:560
	ds_read_b128 v[50:53], v74 offset:16896
	s_waitcnt lgkmcnt(5)
	v_add_f32_e64 v70, v70, -v68
	v_add_f32_e64 v71, v71, -v68
	s_waitcnt lgkmcnt(4)
	v_fma_f32 v70, v70, v10, v68
	v_fma_f32 v71, v71, v11, v68
	s_waitcnt lgkmcnt(0)
	v_fma_f32 v10, v70, v50, 0
	v_fma_f32 v11, v71, v51, 0
	v_add_f32_e64 v50, v66, -v68
	v_add_f32_e64 v51, v67, -v68
	s_nop 0
	v_fma_f32 v66, v50, v12, v68
	v_fma_f32 v67, v51, v13, v68
	s_nop 0
	v_fma_f32 v50, v66, v52, v10
	v_fma_f32 v51, v67, v53, v11
	ds_read_b128 v[10:13], v74 offset:16912
	v_add_f32_e64 v52, v54, -v68
	v_add_f32_e64 v53, v55, -v68
	s_nop 0
	v_fma_f32 v54, v52, v14, v68
	v_fma_f32 v55, v53, v15, v68
	v_add_f32_e64 v14, v56, -v68
	v_add_f32_e64 v15, v57, -v68
	s_waitcnt lgkmcnt(0)
	v_fma_f32 v10, v54, v10, v50
	v_fma_f32 v11, v55, v11, v51
	v_fma_f32 v56, v14, v16, v68
	v_fma_f32 v57, v15, v17, v68
	v_add_f32_e64 v16, v58, -v68
	v_add_f32_e64 v17, v59, -v68
	v_fma_f32 v14, v56, v12, v10
	v_fma_f32 v15, v57, v13, v11
	ds_read_b128 v[10:13], v74 offset:16928
	v_fma_f32 v58, v16, v18, v68
	v_fma_f32 v59, v17, v19, v68
	v_add_f32_e64 v16, v62, -v68
	v_add_f32_e64 v17, v63, -v68
	s_waitcnt lgkmcnt(0)
	v_fma_f32 v10, v58, v10, v14
	v_fma_f32 v11, v59, v11, v15
	v_add_f32_e64 v14, v60, -v68
	v_add_f32_e64 v15, v61, -v68
	v_fma_f32 v62, v16, v22, v68
	v_fma_f32 v63, v17, v23, v68
	v_fma_f32 v60, v14, v20, v68
	v_fma_f32 v61, v15, v21, v68
	s_nop 0
	v_fma_f32 v14, v60, v12, v10
	v_fma_f32 v15, v61, v13, v11
	ds_read_b128 v[10:13], v74 offset:16944
	s_waitcnt lgkmcnt(0)
	v_fma_f32 v10, v62, v10, v14
	v_fma_f32 v11, v63, v11, v15
	v_add_f32_e64 v14, v64, -v68
	v_add_f32_e64 v15, v65, -v68
	s_nop 0
	v_fma_f32 v64, v14, v24, v68
	v_fma_f32 v65, v15, v25, v68
	s_nop 0
	v_fma_f32 v10, v64, v12, v10
	v_fma_f32 v11, v65, v13, v11
	s_nop 0
	v_add_f32_e32 v10, v10, v11
	ds_write_b32 v48, v10 offset:2048
	ds_read_b32 v68, v49 offset:768
	ds_read_b128 v[10:13], v74 offset:768
	ds_read_b128 v[14:17], v74 offset:784
	ds_read_b128 v[18:21], v74 offset:800
	ds_read_b128 v[22:25], v74 offset:816
	ds_read_b128 v[50:53], v74 offset:17152
	s_waitcnt lgkmcnt(5)
	v_add_f32_e64 v70, v70, -v68
	v_add_f32_e64 v71, v71, -v68
	v_add_f32_e64 v66, v66, -v68
	v_add_f32_e64 v67, v67, -v68
	s_waitcnt lgkmcnt(4)
	v_fma_f32 v10, v70, v10, v68
	v_fma_f32 v11, v71, v11, v68
	v_fma_f32 v12, v66, v12, v68
	v_fma_f32 v13, v67, v13, v68
	s_waitcnt lgkmcnt(0)
	v_fma_f32 v50, v10, v50, 0
	v_fma_f32 v51, v11, v51, 0
	v_add_f32_e64 v54, v54, -v68
	v_add_f32_e64 v55, v55, -v68
	v_fma_f32 v66, v12, v52, v50
	v_fma_f32 v67, v13, v53, v51
	ds_read_b128 v[50:53], v74 offset:17168
	v_fma_f32 v14, v54, v14, v68
	v_fma_f32 v15, v55, v15, v68
	v_add_f32_e64 v54, v56, -v68
	v_add_f32_e64 v55, v57, -v68
	v_add_f32_e64 v56, v58, -v68
	v_add_f32_e64 v57, v59, -v68
	v_fma_f32 v16, v54, v16, v68
	v_fma_f32 v17, v55, v17, v68
	s_waitcnt lgkmcnt(0)
	v_fma_f32 v50, v14, v50, v66
	v_fma_f32 v51, v15, v51, v67
	v_fma_f32 v18, v56, v18, v68
	v_fma_f32 v19, v57, v19, v68
	v_fma_f32 v54, v16, v52, v50
	v_fma_f32 v55, v17, v53, v51
	ds_read_b128 v[50:53], v74 offset:17184
	v_add_f32_e64 v56, v62, -v68
	v_add_f32_e64 v57, v63, -v68
	s_waitcnt lgkmcnt(0)
	v_fma_f32 v50, v18, v50, v54
	v_fma_f32 v51, v19, v51, v55
	v_add_f32_e64 v54, v60, -v68
	v_add_f32_e64 v55, v61, -v68
	v_fma_f32 v22, v56, v22, v68
	v_fma_f32 v23, v57, v23, v68
	v_fma_f32 v20, v54, v20, v68
	v_fma_f32 v21, v55, v21, v68
	s_nop 0
	v_fma_f32 v54, v20, v52, v50
	v_fma_f32 v55, v21, v53, v51
	ds_read_b128 v[50:53], v74 offset:17200
	s_waitcnt lgkmcnt(0)
	v_fma_f32 v50, v22, v50, v54
	v_fma_f32 v51, v23, v51, v55
	v_add_f32_e64 v54, v64, -v68
	v_add_f32_e64 v55, v65, -v68
	s_nop 0
	v_fma_f32 v24, v54, v24, v68
	v_fma_f32 v25, v55, v25, v68
	s_nop 0
	v_fma_f32 v50, v24, v52, v50
	v_fma_f32 v51, v25, v53, v51
	s_nop 0
	v_add_f32_e32 v49, v50, v51
	ds_write_b32 v48, v49 offset:3072
	v_add_u32_e32 v48, 0x1000, v48
	s_cbranch_scc0 .LBB0_167
	v_add_u32_e32 v50, v2, v27
	s_waitcnt lgkmcnt(0)
	s_barrier
	ds_read2st64_b32 v[48:49], v50 offset0:96 offset1:97
	s_mov_b32 s56, 32
	s_mov_b64 s[52:53], 0
	s_and_b64 vcc, exec, s[36:37]
	s_waitcnt lgkmcnt(0)
	v_add_f32_e32 v51, v48, v49
	ds_read2st64_b32 v[48:49], v50 offset0:98 offset1:99
	s_waitcnt lgkmcnt(0)
	v_add_f32_e32 v48, v51, v48
	v_add_f32_e32 v50, v48, v49
	v_add_u32_e32 v48, v47, v26
	v_xad_u32 v49, v48, -1, v28
	v_cndmask_b32_e64 v48, v49, v48, s[34:35]
	v_ashrrev_i32_e32 v49, 31, v48
	v_lshl_add_u64 v[48:49], v[4:5], 0, v[48:49]
	v_lshlrev_b64 v[48:49], 10, v[48:49]
	v_lshl_add_u64 v[48:49], v[6:7], 0, v[48:49]
	global_store_dword v[48:49], v50, off
	ds_read2st64_b32 v[48:49], v40 offset0:96 offset1:97
	s_waitcnt lgkmcnt(0)
	v_add_f32_e32 v50, v48, v49
	ds_read2st64_b32 v[48:49], v40 offset0:98 offset1:99
	s_waitcnt lgkmcnt(0)
	v_add_f32_e32 v48, v50, v48
	v_add_f32_e32 v50, v48, v49
	v_add_u32_e32 v48, v47, v1
	v_xad_u32 v49, v48, -1, v28
	v_cndmask_b32_e64 v48, v49, v48, s[34:35]
	v_ashrrev_i32_e32 v49, 31, v48
	v_lshl_add_u64 v[48:49], v[4:5], 0, v[48:49]
	v_lshlrev_b64 v[48:49], 10, v[48:49]
	v_lshl_add_u64 v[48:49], v[6:7], 0, v[48:49]
	global_store_dword v[48:49], v50, off
	ds_read2st64_b32 v[48:49], v41 offset0:96 offset1:97
	s_waitcnt lgkmcnt(0)
	v_add_f32_e32 v50, v48, v49
	ds_read2st64_b32 v[48:49], v41 offset0:98 offset1:99
	s_waitcnt lgkmcnt(0)
	v_add_f32_e32 v48, v50, v48
	v_add_f32_e32 v50, v48, v49
	v_add_u32_e32 v48, v47, v3
	v_xad_u32 v49, v48, -1, v28
	v_cndmask_b32_e64 v48, v49, v48, s[34:35]
	v_ashrrev_i32_e32 v49, 31, v48
	v_lshl_add_u64 v[48:49], v[4:5], 0, v[48:49]
	v_lshlrev_b64 v[48:49], 10, v[48:49]
	v_lshl_add_u64 v[48:49], v[6:7], 0, v[48:49]
	global_store_dword v[48:49], v50, off
	ds_read2st64_b32 v[48:49], v42 offset0:96 offset1:97
	s_waitcnt lgkmcnt(0)
	v_add_f32_e32 v50, v48, v49
	ds_read2st64_b32 v[48:49], v42 offset0:98 offset1:99
	s_waitcnt lgkmcnt(0)
	v_add_f32_e32 v48, v50, v48
	v_add_f32_e32 v50, v48, v49
	v_add_u32_e32 v48, v47, v33
	v_xad_u32 v49, v48, -1, v28
	v_cndmask_b32_e64 v48, v49, v48, s[34:35]
	v_ashrrev_i32_e32 v49, 31, v48
	v_lshl_add_u64 v[48:49], v[4:5], 0, v[48:49]
	v_lshlrev_b64 v[48:49], 10, v[48:49]
	v_lshl_add_u64 v[48:49], v[6:7], 0, v[48:49]
	global_store_dword v[48:49], v50, off
	ds_read2st64_b32 v[48:49], v43 offset0:96 offset1:97
	s_waitcnt lgkmcnt(0)
	v_add_f32_e32 v50, v48, v49
	ds_read2st64_b32 v[48:49], v43 offset0:98 offset1:99
	s_waitcnt lgkmcnt(0)
	v_add_f32_e32 v48, v50, v48
	v_add_f32_e32 v50, v48, v49
	v_add_u32_e32 v48, v47, v34
	v_xad_u32 v49, v48, -1, v28
	v_cndmask_b32_e64 v48, v49, v48, s[34:35]
	v_ashrrev_i32_e32 v49, 31, v48
	v_lshl_add_u64 v[48:49], v[4:5], 0, v[48:49]
	v_lshlrev_b64 v[48:49], 10, v[48:49]
	v_lshl_add_u64 v[48:49], v[6:7], 0, v[48:49]
	global_store_dword v[48:49], v50, off
	ds_read2st64_b32 v[48:49], v44 offset0:96 offset1:97
	s_waitcnt lgkmcnt(0)
	v_add_f32_e32 v50, v48, v49
	ds_read2st64_b32 v[48:49], v44 offset0:98 offset1:99
	s_waitcnt lgkmcnt(0)
	v_add_f32_e32 v48, v50, v48
	v_add_f32_e32 v50, v48, v49
	v_add_u32_e32 v48, v47, v35
	v_xad_u32 v49, v48, -1, v28
	v_cndmask_b32_e64 v48, v49, v48, s[34:35]
	v_ashrrev_i32_e32 v49, 31, v48
	v_lshl_add_u64 v[48:49], v[4:5], 0, v[48:49]
	v_lshlrev_b64 v[48:49], 10, v[48:49]
	v_lshl_add_u64 v[48:49], v[6:7], 0, v[48:49]
	global_store_dword v[48:49], v50, off
	ds_read2st64_b32 v[48:49], v45 offset0:96 offset1:97
	s_waitcnt lgkmcnt(0)
	v_add_f32_e32 v50, v48, v49
	ds_read2st64_b32 v[48:49], v45 offset0:98 offset1:99
	s_waitcnt lgkmcnt(0)
	v_add_f32_e32 v48, v50, v48
	v_add_f32_e32 v50, v48, v49
	v_add_u32_e32 v48, v47, v36
	v_xad_u32 v49, v48, -1, v28
	v_cndmask_b32_e64 v48, v49, v48, s[34:35]
	v_ashrrev_i32_e32 v49, 31, v48
	v_lshl_add_u64 v[48:49], v[4:5], 0, v[48:49]
	v_lshlrev_b64 v[48:49], 10, v[48:49]
	v_lshl_add_u64 v[48:49], v[6:7], 0, v[48:49]
	global_store_dword v[48:49], v50, off
	ds_read2st64_b32 v[48:49], v46 offset0:96 offset1:97
	v_add_u32_e32 v47, v47, v37
	s_waitcnt lgkmcnt(0)
	v_add_f32_e32 v50, v48, v49
	ds_read2st64_b32 v[48:49], v46 offset0:98 offset1:99
	s_waitcnt lgkmcnt(0)
	v_add_f32_e32 v48, v50, v48
	v_add_f32_e32 v50, v48, v49
	v_xad_u32 v48, v47, -1, v28
	v_cndmask_b32_e64 v48, v48, v47, s[34:35]
	v_ashrrev_i32_e32 v49, 31, v48
	v_lshl_add_u64 v[48:49], v[4:5], 0, v[48:49]
	v_lshlrev_b64 v[48:49], 10, v[48:49]
	v_lshl_add_u64 v[48:49], v[6:7], 0, v[48:49]
	global_store_dword v[48:49], v50, off
	s_cbranch_vccz .LBB0_166
